# adds: next work-item index fetched during the last key tile of the current item (differential + dilated queues)
# speedup vs baseline: 1.0052x; 1.0052x over previous
; DI void attn_phase(const Params& p, int layer, char* smem) {
;   int* counter = (int*)(p.ws + OFF_MISC) + layer * 4;
;   volatile int* s_item = (volatile int*)(smem + FLG);
;   for (;;) {
;     __syncthreads();
;     if (threadIdx.x == 0) *s_item = atomicAdd(counter, 1);
.LBB0_173:
	v_writelane_b32 v242, s91, 0
	s_or_b64 exec, exec, s[0:1]
	s_add_u32 s28, s24, 0xef00000
	s_addc_u32 s29, s25, 0
	s_add_u32 s34, s24, 0xef00230
	s_addc_u32 s35, s25, 0
	v_mbcnt_hi_u32_b32 v164, -1, v144
	s_mov_b64 s[6:7], src_shared_base
	s_add_u32 s16, s24, 0xb000000
	s_mov_b32 s52, 0x41c00000
	s_mov_b32 s54, 2.0
	s_mov_b32 s56, 0x41000000
	s_mov_b32 s58, 0x41200000
	s_mov_b32 s60, 0x41800000
	s_mov_b32 s62, 0x41900000
	s_mov_b32 s64, 0x41d00000
	v_and_b32_e32 v0, 64, v164
	s_addc_u32 s17, s25, 0
	s_mov_b64 s[36:37], 0
	v_mov_b32_e32 v1, 0
	v_mov_b32_e32 v122, 0x24000
	v_mov_b32_e32 v125, s7
	v_mov_b32_e32 v126, 0x24000
	v_mov_b32_e32 v127, s7
	s_movk_i32 s6, 0x180
	s_movk_i32 s33, 0x80
	s_movk_i32 s82, 0x7f
	s_movk_i32 s83, 0xff
	s_movk_i32 s84, 0x13f
	s_movk_i32 s85, 0x1800
	s_mov_b32 s86, 0x3fb8aa3b
	s_mov_b32 s87, 0xf800000
	v_mov_b32_e32 v167, 0x260
	v_mov_b32_e32 v168, 0x3c23d70a
	s_mov_b32 s53, 0x41c80000
	s_mov_b32 s55, 0x40400000
	s_mov_b32 s57, 0x41100000
	s_mov_b32 s59, 0x41300000
	s_mov_b32 s61, 0x41880000
	s_mov_b32 s63, 0x41980000
	s_mov_b32 s65, 0x41d80000
	s_mov_b32 s88, 0xc2ce8ed0
	s_mov_b32 s89, 0x42b17218
	v_mov_b32_e32 v128, 0x3e4ccccc
	s_movk_i32 s90, 0x880
	s_mov_b64 s[66:67], 0xcc00300
	v_mov_b32_e32 v169, 0x358637bd
	s_mov_b32 s91, 0x800000
	s_mov_b32 s92, 0xcc00000
	s_mov_b32 s93, 0x10800
	s_mov_b64 s[68:69], 0x8000
	s_mov_b32 s94, 0x8000
	v_mov_b32_e32 v170, 0x200
	v_xor_b32_e32 v159, 32, v164
	v_add_u32_e32 v165, 64, v0
	v_xor_b32_e32 v160, 16, v164
	v_xor_b32_e32 v161, 8, v164
	v_xor_b32_e32 v162, 4, v164
	v_xor_b32_e32 v163, 2, v164
	v_xor_b32_e32 v166, 1, v164
	v_mov_b32_e32 v124, 0x24060
	v_mov_b32_e32 v130, 0x24064
	v_mov_b32_e32 v132, 0x24068
	v_mov_b32_e32 v134, 0x2406c
	v_mov_b32_e32 v136, 0x24070
	v_mov_b32_e32 v138, 0x24074
	v_mov_b32_e32 v140, 0x24078
	v_mov_b32_e32 v142, 0x2407c
	v_mov_b32_e32 v171, 0xf149f2ca
	v_mov_b32_e32 v172, 0x7f800000
	s_barrier
	s_mov_b32 s101, 0
	s_branch .LBB0_177

; DI void attn_phase(const Params& p, int layer, char* smem) {
;     ...
;   for (;;) {
;     __syncthreads();
;     if (threadIdx.x == 0) *s_item = atomicAdd(counter, 1);
;     __syncthreads();
;     const int item = *s_item;
.LBB0_177:
	s_barrier
	s_and_saveexec_b64 s[0:1], s[8:9]
	s_cbranch_execz .LBB0_181
	s_cmp_eq_u32 s101, 1
	s_cbranch_scc1 .Llpf1_have
	v_mov_b32_e32 v254, 1
	global_atomic_add v255, v1, v254, s[28:29] sc0
.Llpf1_have:
	s_mov_b32 s101, 0
	s_waitcnt vmcnt(0)
	ds_write_b32 v122, v255
	s_waitcnt lgkmcnt(0)

; template <int TYPE>
; DI void attn_item(const Params& p, int layer, int head, int qt, int dil, int res, int chunk, char* smem) {
;     ...
;     __syncthreads();
;     if (TYPE == 2) {
;       if ((sflag[0] & sflag[1] & sflag[2] & sflag[3] & sflag[4] & sflag[5] & sflag[6] & sflag[7]) != 0) break;
;     }
;     *(uint4*)(sK + swz(kkey0, kchunk)) = kreg0;
;     ...
;     ATT_VSTORE(vreg0, vdc0)
;     __syncthreads();
;     ATT_PREFETCH((kt > kt_lo) ? kt - 1 : kt);
;     __builtin_amdgcn_sched_barrier(0);
;     const int Kb = kt * 64;
; #pragma unroll
;     ...
;       const int Ks = Kb + 32 * sub;
;       bool need;
;       if (TYPE == 0) need = (Ks <= wq0 + 31) && (Ks + 31 >= wq0 - 128);
;       else if (TYPE == 1) need = (Ks <= wq0 + 31);
;       else need = (Ks < wq0 + 31) && (sflag[wid] == 0);
;       if (!need) continue;
;       const int db = Uq - Ks - 4 * h;
;       f32x16 s1, s2;
;       if (TYPE == 2) {
; #pragma unroll
;         for (int i = 0; i < 16; ++i) { s1[i] = 0.f; s2[i] = 0.f; }
;       } else {
;         const float base = -slope * (float)db - cref;
;         const bool msk = (TYPE == 0) ? true : (__builtin_amdgcn_readfirstlane((Ks + 31 > wq0) ? 1 : 0) != 0);
;         if (msk) {
; #pragma unroll
;           for (int i = 0; i < 16; ++i) {
;             const int ci = (i & 3) + 8 * (i >> 2);
;             const int dist = db - ci;
;             s1[i] = (dist >= 0 && dist <= wlim) ? fmaf(slope, (float)ci, base) : -1e30f;
;             s2[i] = s1[i];
;           }
.LBB0_202:
	v_cmp_gt_i32_e32 vcc, v133, v152
	s_barrier
	s_nop 0
	v_subbrev_co_u32_e32 v0, vcc, 0, v133, vcc
	v_lshlrev_b32_e32 v0, 6, v0
	v_add_u32_e32 v66, v0, v137
	v_or_b32_e32 v0, v0, v177
	v_mad_i64_i32 v[66:67], s[4:5], v66, s85, v[154:155]
	s_waitcnt vmcnt(0)
	ds_write_b128 v186, v[118:121]
	ds_write_b16 v187, v114 offset:8192
	ds_write_b16_d16_hi v187, v114 offset:8320
	ds_write_b16 v188, v115 offset:8192
	ds_write_b16_d16_hi v189, v115 offset:8192
	ds_write_b16 v190, v116 offset:8192
	ds_write_b16_d16_hi v191, v116 offset:8192
	ds_write_b16 v192, v117 offset:8192
	ds_write_b16_d16_hi v193, v117 offset:8192
	s_waitcnt lgkmcnt(0)
	s_barrier
	v_mad_i64_i32 v[68:69], s[4:5], v0, s85, v[156:157]
	global_load_dwordx4 v[118:121], v[66:67], off
	global_load_dwordx4 v[114:117], v[68:69], off
	v_cmp_le_i32_e64 s[4:5], v133, v152
	s_and_b64 s[98:99], s[4:5], exec
	s_cbranch_scc0 .Llpf1_nl
	s_mov_b32 s101, 1
	s_and_saveexec_b64 s[98:99], s[8:9]
	s_cbranch_execz .Llpf1_sk
	v_mov_b32_e32 v254, 1
	global_atomic_add v255, v1, v254, s[28:29] sc0
.Llpf1_sk:
	s_or_b64 exec, exec, s[98:99]
.Llpf1_nl:
	v_add_u32_e32 v0, 32, v139
	v_cmp_le_i32_e32 vcc, v0, v141
	s_and_saveexec_b64 s[76:77], vcc
	s_cbranch_execz .LBB0_208
	v_subrev_u32_e32 v82, 32, v185
	v_add_u32_e32 v66, 63, v139
	v_cvt_f32_i32_e32 v0, v82
	v_cmp_gt_i32_e32 vcc, v66, v176
	s_mov_b64 s[78:79], -1
	v_fma_f32 v0, -v146, v0, -v135
	v_cndmask_b32_e64 v66, 0, 1, vcc
	v_add_f32_e32 v67, v146, v0
	v_readfirstlane_b32 s10, v66
	s_bitcmp1_b32 s10, 0
	s_cselect_b64 s[96:97], -1, 0
	s_and_b64 vcc, exec, s[96:97]
	v_fma_f32 v66, 0, v146, v0
	s_cbranch_vccnz .LBB0_205
	v_pk_fma_f32 v[68:69], v[146:147], s[54:55], v[0:1] op_sel_hi:[1,1,0]
	v_pk_fma_f32 v[70:71], v[146:147], s[56:57], v[0:1] op_sel_hi:[1,1,0]
	v_pk_fma_f32 v[72:73], v[146:147], s[58:59], v[0:1] op_sel_hi:[1,1,0]
	v_pk_fma_f32 v[74:75], v[146:147], s[60:61], v[0:1] op_sel_hi:[1,1,0]
	v_pk_fma_f32 v[76:77], v[146:147], s[62:63], v[0:1] op_sel_hi:[1,1,0]
	v_pk_fma_f32 v[78:79], v[146:147], s[52:53], v[0:1] op_sel_hi:[1,1,0]
	v_pk_fma_f32 v[80:81], v[146:147], s[64:65], v[0:1] op_sel_hi:[1,1,0]
	s_mov_b64 s[78:79], 0

; DI void attn_phase(const Params& p, int layer, char* smem) {
;     ...
;   for (;;) {
;     __syncthreads();
;     if (threadIdx.x == 0) *s_item = atomicAdd(counter + 2, 1);
;     __syncthreads();
;     const int j = *s_item;
;     if (j >= 1152) break;
.LBB0_245:
	s_or_b64 exec, exec, s[36:37]
	s_add_u32 s4, s24, 0xef00008
	s_addc_u32 s5, s25, 0
	s_mov_b64 s[0:1], src_shared_base
	s_add_u32 s28, s24, 0xef04000
	s_mov_b32 s34, 2.0
	s_mov_b32 s36, 0x41000000
	s_mov_b32 s52, 0x41200000
	s_mov_b32 s54, 0x41800000
	s_mov_b32 s56, 0x41900000
	s_mov_b32 s58, 0x41c00000
	s_mov_b32 s60, 0x41d00000
	s_addc_u32 s29, s25, 0
	s_mov_b64 s[6:7], 0
	s_waitcnt vmcnt(0)
	v_mov_b32_e32 v73, 0
	v_mov_b32_e32 v74, 0x24000
	v_mov_b32_e32 v77, s1
	v_mov_b32_e32 v76, 0x24000
	s_movk_i32 s33, 0x480
	s_mov_b32 s68, 0x2aaaaaab
	s_mov_b32 s69, 0x55555556
	s_mov_b32 s70, 0x38e38e39
	s_movk_i32 s71, 0x1800
	s_mov_b32 s72, 0x40c00000
	s_mov_b32 s73, 0xc2fc0000
	s_mov_b32 s74, 0xf800000
	v_mov_b32_e32 v94, 0x260
	v_mov_b32_e32 v95, 0x3c23d70a
	s_movk_i32 s75, 0x300
	s_movk_i32 s76, 0x81
	s_mov_b32 s35, 0x40400000
	s_mov_b32 s37, 0x41100000
	s_mov_b32 s53, 0x41300000
	s_mov_b32 s55, 0x41880000
	s_mov_b32 s57, 0x41980000
	s_mov_b32 s59, 0x41c80000
	s_mov_b32 s61, 0x41d80000
	s_mov_b32 s77, 0xc00000
	v_mov_b32_e32 v96, 0x42800000
	v_not_b32_e32 v97, 63
	v_mov_b32_e32 v98, 0xf149f2ca
	s_mov_b32 s101, 0
	s_branch .LBB0_248

; DI void attn_phase(const Params& p, int layer, char* smem) {
;     ...
;   for (;;) {
;     __syncthreads();
;     if (threadIdx.x == 0) *s_item = atomicAdd(counter + 2, 1);
;     __syncthreads();
;     const int j = *s_item;
.LBB0_248:
	s_waitcnt lgkmcnt(0)
	s_barrier
	s_and_saveexec_b64 s[0:1], s[8:9]
	s_cbranch_execz .LBB0_252
	s_cmp_eq_u32 s101, 1
	s_cbranch_scc1 .Llpf2_have
	v_mov_b32_e32 v254, 1
	global_atomic_add v255, v73, v254, s[4:5] sc0
.Llpf2_have:
	s_mov_b32 s101, 0
	s_waitcnt vmcnt(0)
	ds_write_b32 v74, v255
	s_waitcnt lgkmcnt(0)

; template <int TYPE>
; DI void attn_item(const Params& p, int layer, int head, int qt, int dil, int res, int chunk, char* smem) {
;     ...
;     __syncthreads();
;     if (TYPE == 2) {
;       if ((sflag[0] & sflag[1] & sflag[2] & sflag[3] & sflag[4] & sflag[5] & sflag[6] & sflag[7]) != 0) break;
;     }
;     *(uint4*)(sK + swz(kkey0, kchunk)) = kreg0;
;     ...
;     ATT_VSTORE(vreg0, vdc0)
;     __syncthreads();
;     ATT_PREFETCH((kt > kt_lo) ? kt - 1 : kt);
.LBB0_256:
	v_cmp_gt_i32_e32 vcc, v99, v100
	s_barrier
	s_nop 0
	v_subbrev_co_u32_e32 v32, vcc, 0, v99, vcc
	v_lshlrev_b32_e32 v34, 6, v32
	v_add_u32_e32 v32, v34, v101
	v_ashrrev_i32_e32 v33, 31, v32
	v_or_b32_e32 v34, v34, v75
	v_lshlrev_b64 v[32:33], v79, v[32:33]
	v_ashrrev_i32_e32 v35, 31, v34
	v_lshl_add_u64 v[32:33], v[32:33], 0, v[86:87]
	v_lshlrev_b64 v[34:35], v79, v[34:35]
	v_lshl_add_u64 v[34:35], v[34:35], 0, v[86:87]
	v_mad_u64_u32 v[36:37], s[0:1], v32, s71, v[88:89]
	v_mad_i32_i24 v37, v33, s71, v37
	v_mad_u64_u32 v[32:33], s[0:1], v34, s71, v[90:91]
	s_waitcnt vmcnt(0)
	ds_write_b128 v108, v[68:71]
	ds_write_b16 v109, v64 offset:8192
	ds_write_b16_d16_hi v109, v64 offset:8320
	ds_write_b16 v110, v65 offset:8192
	ds_write_b16_d16_hi v111, v65 offset:8192
	ds_write_b16 v112, v66 offset:8192
	ds_write_b16_d16_hi v113, v66 offset:8192
	ds_write_b16 v114, v67 offset:8192
	ds_write_b16_d16_hi v115, v67 offset:8192
	s_waitcnt lgkmcnt(0)
	s_barrier
	v_mad_i32_i24 v33, v35, s71, v33
	global_load_dwordx4 v[68:71], v[36:37], off
	global_load_dwordx4 v[64:67], v[32:33], off
	v_cmp_le_i32_e32 vcc, v99, v100
	s_and_b64 s[98:99], vcc, exec
	s_cbranch_scc0 .Llpf2_nl
	s_mov_b32 s101, 1
	s_and_saveexec_b64 s[98:99], s[8:9]
	s_cbranch_execz .Llpf2_sk
	v_mov_b32_e32 v254, 1
	global_atomic_add v255, v73, v254, s[4:5] sc0

; template <int TYPE>
; DI void attn_item(const Params& p, int layer, int head, int qt, int dil, int res, int chunk, char* smem) {
;     ...
;       const int Ks = Kb + 32 * sub;
;       bool need;
;       if (TYPE == 0) need = (Ks <= wq0 + 31) && (Ks + 31 >= wq0 - 128);
;       else if (TYPE == 1) need = (Ks <= wq0 + 31);
;       else need = (Ks < wq0 + 31) && (sflag[wid] == 0);
;       if (!need) continue;
;       const int db = Uq - Ks - 4 * h;
;       f32x16 s1, s2;
;       if (TYPE == 2) {
; #pragma unroll
;         for (int i = 0; i < 16; ++i) { s1[i] = 0.f; s2[i] = 0.f; }
;       } else {
;         const float base = -slope * (float)db - cref;
;         const bool msk = (TYPE == 0) ? true : (__builtin_amdgcn_readfirstlane((Ks + 31 > wq0) ? 1 : 0) != 0);
;         if (msk) {
; #pragma unroll
;           for (int i = 0; i < 16; ++i) {
;             const int ci = (i & 3) + 8 * (i >> 2);
;             const int dist = db - ci;
;             s1[i] = (dist >= 0 && dist <= wlim) ? fmaf(slope, (float)ci, base) : -1e30f;
;             s2[i] = s1[i];
;           }
;         } else {
; #pragma unroll
;           for (int i = 0; i < 16; ++i) {
;             const int ci = (i & 3) + 8 * (i >> 2);
;             s1[i] = fmaf(slope, (float)ci, base);
;             s2[i] = s1[i];
;           }
;         }
;       }
;       {
;         bf16x8 kf[4];
; #pragma unroll
;         for (int ks = 0; ks < 4; ++ks) kf[ks] = *(const bf16x8*)(sK + swz(32 * sub + ql, 2 * ks + h));
;         if (TYPE == 1) {
;           s1 = mfma32(kf[0], qf[0], s1);
;           s1 = mfma32(kf[1], qf[1], s1);
;           s2 = mfma32(kf[2], qf[2], s2);
;           s2 = mfma32(kf[3], qf[3], s2);
;         } else {
; #pragma unroll
;           for (int ks = 0; ks < 4; ++ks) s1 = mfma32(kf[ks], qf[ks], s1);
;         }
;       }
;       bf16x8 vf[2][2];
; #pragma unroll
;       for (int s = 0; s < 2; ++s)
; #pragma unroll
;         for (int dt = 0; dt < 2; ++dt) vf[s][dt] = *(const bf16x8*)(sV + swz(32 * dt + ql, 4 * sub + 2 * s + h));
;       if (TYPE == 0 || TYPE == 1) {
;         const bool masked = (TYPE == 0) ? true : (Ks + 31 > wq0);
;         bf16x8 pk0, pk1;
;         fx_step(s1, l1, db, masked, wlim, pk0, pk1);
;         O1a = mfma32(vf[0][0], pk0, O1a);
;         O1b = mfma32(vf[0][1], pk0, O1b);
;         O1a = mfma32(vf[1][0], pk1, O1a);
;         O1b = mfma32(vf[1][1], pk1, O1b);
.Llpf2_nl:
	v_add_u32_e32 v32, 1, v107
	v_cmp_le_i32_e64 s[0:1], v32, v102
	v_add_u32_e32 v32, 32, v107
	v_cmp_ge_i32_e64 s[2:3], v32, v103
	s_and_b64 s[0:1], s[0:1], s[2:3]
	s_and_saveexec_b64 s[2:3], s[0:1]
	s_cbranch_execz .LBB0_258
	v_add_u32_e32 v32, 1, v106
	v_cvt_f32_i32_e32 v33, v32
	v_cmp_gt_u32_e64 s[0:1], s76, v32
	v_add_u32_e32 v36, -2, v106
	v_add_u32_e32 v37, -1, v106
	v_fma_f32 v46, -v92, v33, -v105
	v_fma_f32 v33, 0, v92, v46
	v_add_f32_e32 v34, v92, v46
	v_cndmask_b32_e64 v32, v98, v33, s[0:1]
	v_cmp_gt_u32_e64 s[0:1], s76, v106
	v_add_u32_e32 v38, -8, v106
	v_add_u32_e32 v39, -7, v106
	v_cndmask_b32_e64 v33, v98, v34, s[0:1]
	v_pk_fma_f32 v[34:35], v[92:93], s[34:35], v[46:47] op_sel_hi:[1,1,0]
	v_cmp_gt_u32_e64 s[0:1], s76, v36
	v_add_u32_e32 v40, -10, v106
	v_add_u32_e32 v41, -9, v106
	v_cndmask_b32_e64 v35, v98, v35, s[0:1]
	v_cmp_gt_u32_e64 s[0:1], s76, v37
	v_pk_fma_f32 v[36:37], v[92:93], s[36:37], v[46:47] op_sel_hi:[1,1,0]
	v_add_u32_e32 v42, -16, v106
	v_cndmask_b32_e64 v34, v98, v34, s[0:1]
	v_cmp_gt_u32_e64 s[0:1], s76, v38
	v_add_u32_e32 v43, -15, v106
	v_subrev_u32_e32 v44, 18, v106
	v_cndmask_b32_e64 v37, v98, v37, s[0:1]
	v_cmp_gt_u32_e64 s[0:1], s76, v39
	v_pk_fma_f32 v[38:39], v[92:93], s[52:53], v[46:47] op_sel_hi:[1,1,0]
	v_subrev_u32_e32 v45, 17, v106
	v_cndmask_b32_e64 v36, v98, v36, s[0:1]
	v_cmp_gt_u32_e64 s[0:1], s76, v40
	v_subrev_u32_e32 v120, 23, v106
	v_subrev_u32_e32 v124, 26, v106
	v_cndmask_b32_e64 v39, v98, v39, s[0:1]
	v_cmp_gt_u32_e64 s[0:1], s76, v41
	v_pk_fma_f32 v[40:41], v[92:93], s[54:55], v[46:47] op_sel_hi:[1,1,0]
	v_subrev_u32_e32 v125, 25, v106
	v_cndmask_b32_e64 v38, v98, v38, s[0:1]
	v_cmp_gt_u32_e64 s[0:1], s76, v42
	s_nop 1
	v_cndmask_b32_e64 v41, v98, v41, s[0:1]
	v_cmp_gt_u32_e64 s[0:1], s76, v43
	v_pk_fma_f32 v[42:43], v[92:93], s[56:57], v[46:47] op_sel_hi:[1,1,0]
	v_subrev_u32_e32 v47, 24, v106
	v_cndmask_b32_e64 v40, v98, v40, s[0:1]
	v_cmp_gt_u32_e64 s[0:1], s76, v44
	s_nop 1
	v_cndmask_b32_e64 v43, v98, v43, s[0:1]
	v_cmp_gt_u32_e64 s[0:1], s76, v45
	v_pk_fma_f32 v[44:45], v[92:93], s[58:59], v[46:47] op_sel_hi:[1,1,0]
	s_nop 0
	v_cndmask_b32_e64 v42, v98, v42, s[0:1]
	v_cmp_gt_u32_e64 s[0:1], s76, v47
	v_pk_fma_f32 v[46:47], v[92:93], s[60:61], v[46:47] op_sel_hi:[1,1,0]
	s_nop 0
	v_cndmask_b32_e64 v45, v98, v45, s[0:1]
	v_cmp_gt_u32_e64 s[0:1], s76, v120
	ds_read_b128 v[120:123], v116 offset:4096
	s_nop 0
	v_cndmask_b32_e64 v44, v98, v44, s[0:1]
	v_cmp_gt_u32_e64 s[0:1], s76, v124
	s_nop 1
	v_cndmask_b32_e64 v47, v98, v47, s[0:1]
	v_cmp_gt_u32_e64 s[0:1], s76, v125
	ds_read_b128 v[124:127], v117 offset:4096
	s_nop 0
	v_cndmask_b32_e64 v46, v98, v46, s[0:1]
	s_waitcnt lgkmcnt(1)
	s_nop 0
	v_mfma_f32_32x32x16_bf16 v[32:47], v[120:123], v[48:51], v[32:47]
	s_waitcnt lgkmcnt(0)
	v_mfma_f32_32x32x16_bf16 v[32:47], v[124:127], v[52:55], v[32:47]
	ds_read_b128 v[120:123], v118 offset:4096
	ds_read_b128 v[124:127], v118 offset:8192
	s_waitcnt lgkmcnt(1)
	v_mfma_f32_32x32x16_bf16 v[32:47], v[120:123], v[56:59], v[32:47]
	ds_read_b128 v[120:123], v119 offset:4096
	ds_read_b128 v[128:131], v118 offset:12288
	s_waitcnt lgkmcnt(1)
	v_mfma_f32_32x32x16_bf16 v[32:47], v[120:123], v[60:63], v[32:47]
	ds_read_b128 v[120:123], v119 offset:8192
	ds_read_b128 v[132:135], v119 offset:12288
	s_nop 9
	v_exp_f32_e32 v32, v32
	v_exp_f32_e32 v33, v33
	v_exp_f32_e32 v34, v34
	v_exp_f32_e32 v35, v35
	v_exp_f32_e32 v36, v36
	v_exp_f32_e32 v37, v37
	v_exp_f32_e32 v38, v38
	v_exp_f32_e32 v39, v39
	v_add_f32_e32 v136, 0, v32
	v_add_f32_e32 v136, v33, v136
	v_add_f32_e32 v136, v34, v136
	v_add_f32_e32 v136, v35, v136
	v_cvt_pk_bf16_f32 v32, v32, v33
	v_cvt_pk_bf16_f32 v33, v34, v35
	v_cvt_pk_bf16_f32 v34, v36, v37
	v_cvt_pk_bf16_f32 v35, v38, v39
	v_add_f32_e32 v136, v36, v136
	v_add_f32_e32 v136, v37, v136
	v_mfma_f32_32x32x16_bf16 v[16:31], v[124:127], v[32:35], v[16:31]
	v_add_f32_e32 v36, v38, v136
	v_exp_f32_e32 v40, v40
	v_exp_f32_e32 v41, v41
	v_add_f32_e32 v36, v39, v36
	v_exp_f32_e32 v37, v42
	v_exp_f32_e32 v38, v43
	v_exp_f32_e32 v39, v44
	s_waitcnt lgkmcnt(2)
	v_mfma_f32_32x32x16_bf16 v[0:15], v[128:131], v[32:35], v[0:15]
	v_exp_f32_e32 v42, v45
	v_exp_f32_e32 v43, v46
	v_exp_f32_e32 v44, v47
	v_add_f32_e32 v36, v40, v36
	v_cvt_pk_bf16_f32 v32, v40, v41
	v_cvt_pk_bf16_f32 v33, v37, v38
	v_cvt_pk_bf16_f32 v34, v39, v42
	v_cvt_pk_bf16_f32 v35, v43, v44
	v_add_f32_e32 v36, v41, v36
	v_add_f32_e32 v36, v37, v36
	s_waitcnt lgkmcnt(1)
	v_mfma_f32_32x32x16_bf16 v[16:31], v[120:123], v[32:35], v[16:31]
	v_add_f32_e32 v36, v38, v36
	v_add_f32_e32 v36, v39, v36
	v_add_f32_e32 v36, v42, v36
	v_add_f32_e32 v36, v43, v36
	v_add_f32_e32 v36, v44, v36
	v_add_f32_e32 v104, v104, v36
	s_waitcnt lgkmcnt(0)
	v_mfma_f32_32x32x16_bf16 v[0:15], v[132:135], v[32:35], v[0:15]

; DI void attn_phase(const Params& p, int layer, char* smem) {
;   int* counter = (int*)(p.ws + OFF_MISC) + layer * 4;
;   volatile int* s_item = (volatile int*)(smem + FLG);
;   for (;;) {
;     __syncthreads();
;     if (threadIdx.x == 0) *s_item = atomicAdd(counter, 1);
.LBB0_549:
	s_or_b64 exec, exec, s[0:1]
	s_add_u32 s18, s24, 0xef00010
	s_addc_u32 s19, s25, 0
	s_mov_b64 s[6:7], src_shared_base
	s_add_u32 s36, s24, 0xef002b0
	s_mov_b32 s42, 0x41c00000
	s_mov_b32 s44, 2.0
	s_mov_b32 s46, 0x41000000
	s_mov_b32 s48, 0x41200000
	s_mov_b32 s52, 0x41800000
	s_mov_b32 s54, 0x41900000
	s_mov_b32 s56, 0x41d00000
	s_addc_u32 s37, s25, 0
	s_mov_b64 s[40:41], 0
	v_mov_b32_e32 v1, 0
	v_mov_b32_e32 v122, 0x24000
	v_mov_b32_e32 v125, s7
	v_mov_b32_e32 v126, 0x24000
	v_mov_b32_e32 v127, s7
	s_movk_i32 s6, 0x180
	s_movk_i32 s75, 0x80
	s_movk_i32 s76, 0x7f
	s_movk_i32 s77, 0xff
	s_movk_i32 s78, 0x13f
	s_movk_i32 s79, 0x1800
	s_mov_b32 s80, 0x3fb8aa3b
	s_mov_b32 s81, 0xf800000
	v_mov_b32_e32 v165, 0x260
	v_mov_b32_e32 v166, 0x3c23d70a
	s_mov_b32 s43, 0x41c80000
	s_mov_b32 s45, 0x40400000
	s_mov_b32 s47, 0x41100000
	s_mov_b32 s49, 0x41300000
	s_mov_b32 s53, 0x41880000
	s_mov_b32 s55, 0x41980000
	s_mov_b32 s57, 0x41d80000
	s_mov_b32 s82, 0xc2ce8ed0
	s_mov_b32 s83, 0x42b17218
	v_mov_b32_e32 v128, 0x3eb60549
	s_movk_i32 s84, 0x880
	s_mov_b64 s[58:59], 0xcc00300
	v_mov_b32_e32 v167, 0x358637bd
	s_mov_b32 s85, 0x800000
	s_mov_b32 s86, 0xcc00000
	s_mov_b32 s87, 0x10800
	s_mov_b64 s[60:61], 0x8000
	s_mov_b32 s88, 0x8000
	v_mov_b32_e32 v168, 0x200
	v_mov_b32_e32 v124, 0x24060
	v_mov_b32_e32 v130, 0x24064
	v_mov_b32_e32 v132, 0x24068
	v_mov_b32_e32 v134, 0x2406c
	v_mov_b32_e32 v136, 0x24070
	v_mov_b32_e32 v138, 0x24074
	v_mov_b32_e32 v140, 0x24078
	v_mov_b32_e32 v142, 0x2407c
	v_mov_b32_e32 v169, 0xf149f2ca
	v_mov_b32_e32 v170, 0x7f800000
	s_barrier
	s_mov_b32 s101, 0
	s_branch .LBB0_553

; DI void attn_phase(const Params& p, int layer, char* smem) {
;     ...
;   for (;;) {
;     __syncthreads();
;     if (threadIdx.x == 0) *s_item = atomicAdd(counter, 1);
;     __syncthreads();
;     const int item = *s_item;
.LBB0_553:
	s_barrier
	s_and_saveexec_b64 s[0:1], s[8:9]
	s_cbranch_execz .LBB0_557
	s_cmp_eq_u32 s101, 1
	s_cbranch_scc1 .Llpf3_have
	v_mov_b32_e32 v254, 1
	global_atomic_add v255, v1, v254, s[18:19] sc0

; template <int TYPE>
; DI void attn_item(const Params& p, int layer, int head, int qt, int dil, int res, int chunk, char* smem) {
;     ...
;     __syncthreads();
;     if (TYPE == 2) {
;       if ((sflag[0] & sflag[1] & sflag[2] & sflag[3] & sflag[4] & sflag[5] & sflag[6] & sflag[7]) != 0) break;
;     }
;     *(uint4*)(sK + swz(kkey0, kchunk)) = kreg0;
;     ...
;     ATT_VSTORE(vreg0, vdc0)
;     __syncthreads();
;     ATT_PREFETCH((kt > kt_lo) ? kt - 1 : kt);
.LBB0_578:
	v_cmp_gt_i32_e32 vcc, v133, v152
	s_barrier
	s_nop 0
	v_subbrev_co_u32_e32 v0, vcc, 0, v133, vcc
	v_lshlrev_b32_e32 v0, 6, v0
	v_add_u32_e32 v66, v0, v137
	v_or_b32_e32 v0, v0, v145
	v_mad_i64_i32 v[66:67], s[4:5], v66, s79, v[154:155]
	s_waitcnt vmcnt(0)
	ds_write_b128 v178, v[118:121]
	ds_write_b16 v179, v114 offset:8192
	ds_write_b16_d16_hi v179, v114 offset:8320
	ds_write_b16 v180, v115 offset:8192
	ds_write_b16_d16_hi v181, v115 offset:8192
	ds_write_b16 v182, v116 offset:8192
	ds_write_b16_d16_hi v183, v116 offset:8192
	ds_write_b16 v184, v117 offset:8192
	ds_write_b16_d16_hi v185, v117 offset:8192
	s_waitcnt lgkmcnt(0)
	s_barrier
	v_mad_i64_i32 v[68:69], s[4:5], v0, s79, v[156:157]
	global_load_dwordx4 v[118:121], v[66:67], off
	global_load_dwordx4 v[114:117], v[68:69], off
	v_cmp_le_i32_e64 s[4:5], v133, v152
	s_and_b64 s[98:99], s[4:5], exec
	s_cbranch_scc0 .Llpf3_nl
	s_mov_b32 s101, 1
	s_and_saveexec_b64 s[98:99], s[8:9]
	s_cbranch_execz .Llpf3_sk
	v_mov_b32_e32 v254, 1
	global_atomic_add v255, v1, v254, s[18:19] sc0

; template <int TYPE>
; DI void attn_item(const Params& p, int layer, int head, int qt, int dil, int res, int chunk, char* smem) {
;     ...
;       const int Ks = Kb + 32 * sub;
;       bool need;
;       if (TYPE == 0) need = (Ks <= wq0 + 31) && (Ks + 31 >= wq0 - 128);
;       else if (TYPE == 1) need = (Ks <= wq0 + 31);
;       else need = (Ks < wq0 + 31) && (sflag[wid] == 0);
;       if (!need) continue;
;       const int db = Uq - Ks - 4 * h;
;       f32x16 s1, s2;
;       if (TYPE == 2) {
; #pragma unroll
;         for (int i = 0; i < 16; ++i) { s1[i] = 0.f; s2[i] = 0.f; }
;       } else {
;         const float base = -slope * (float)db - cref;
;         const bool msk = (TYPE == 0) ? true : (__builtin_amdgcn_readfirstlane((Ks + 31 > wq0) ? 1 : 0) != 0);
;         if (msk) {
; #pragma unroll
;           for (int i = 0; i < 16; ++i) {
;             const int ci = (i & 3) + 8 * (i >> 2);
;             const int dist = db - ci;
;             s1[i] = (dist >= 0 && dist <= wlim) ? fmaf(slope, (float)ci, base) : -1e30f;
;             s2[i] = s1[i];
;           }
;         } else {
; #pragma unroll
;           for (int i = 0; i < 16; ++i) {
;             const int ci = (i & 3) + 8 * (i >> 2);
;             s1[i] = fmaf(slope, (float)ci, base);
;             s2[i] = s1[i];
;           }
.Llpf3_nl:
	v_add_u32_e32 v0, 32, v139
	v_cmp_le_i32_e32 vcc, v0, v141
	s_and_saveexec_b64 s[68:69], vcc
	s_cbranch_execz .LBB0_584
	v_subrev_u32_e32 v82, 32, v177
	v_add_u32_e32 v66, 63, v139
	v_cvt_f32_i32_e32 v0, v82
	v_cmp_gt_i32_e32 vcc, v66, v174
	s_mov_b64 s[70:71], -1
	v_fma_f32 v0, -v146, v0, -v135
	v_cndmask_b32_e64 v66, 0, 1, vcc
	v_add_f32_e32 v67, v146, v0
	v_readfirstlane_b32 s10, v66
	s_bitcmp1_b32 s10, 0
	s_cselect_b64 s[90:91], -1, 0
	s_and_b64 vcc, exec, s[90:91]
	v_fma_f32 v66, 0, v146, v0
	s_cbranch_vccnz .LBB0_581
	v_pk_fma_f32 v[68:69], v[146:147], s[44:45], v[0:1] op_sel_hi:[1,1,0]
	v_pk_fma_f32 v[70:71], v[146:147], s[46:47], v[0:1] op_sel_hi:[1,1,0]
	v_pk_fma_f32 v[72:73], v[146:147], s[48:49], v[0:1] op_sel_hi:[1,1,0]
	v_pk_fma_f32 v[74:75], v[146:147], s[52:53], v[0:1] op_sel_hi:[1,1,0]
	v_pk_fma_f32 v[76:77], v[146:147], s[54:55], v[0:1] op_sel_hi:[1,1,0]
	v_pk_fma_f32 v[78:79], v[146:147], s[42:43], v[0:1] op_sel_hi:[1,1,0]
	v_pk_fma_f32 v[80:81], v[146:147], s[56:57], v[0:1] op_sel_hi:[1,1,0]
	s_mov_b64 s[70:71], 0

; DI void attn_phase(const Params& p, int layer, char* smem) {
;     ...
;   for (;;) {
;     __syncthreads();
;     if (threadIdx.x == 0) *s_item = atomicAdd(counter + 2, 1);
;     __syncthreads();
;     const int j = *s_item;
;     if (j >= 1152) break;
.LBB0_621:
	s_or_b64 exec, exec, s[40:41]
	s_mov_b64 s[0:1], src_shared_base
	s_add_u32 s4, s24, 0xef00018
	s_mov_b32 s18, 2.0
	s_mov_b32 s36, 0x41000000
	s_mov_b32 s40, 0x41200000
	s_mov_b32 s42, 0x41800000
	s_mov_b32 s44, 0x41900000
	s_mov_b32 s46, 0x41c00000
	s_mov_b32 s48, 0x41d00000
	s_addc_u32 s5, s25, 0
	s_mov_b64 s[6:7], 0
	s_waitcnt vmcnt(0)
	v_mov_b32_e32 v73, 0
	v_mov_b32_e32 v74, 0x24000
	v_mov_b32_e32 v77, s1
	v_mov_b32_e32 v76, 0x24000
	s_movk_i32 s58, 0x480
	s_mov_b32 s59, 0x2aaaaaab
	s_mov_b32 s60, 0x55555556
	s_mov_b32 s61, 0x38e38e39
	s_movk_i32 s62, 0x1800
	s_mov_b32 s63, 0x40c00000
	s_mov_b32 s64, 0xc2fc0000
	s_mov_b32 s65, 0xf800000
	v_mov_b32_e32 v94, 0x260
	v_mov_b32_e32 v95, 0x3c23d70a
	s_movk_i32 s66, 0x300
	s_movk_i32 s67, 0x81
	s_mov_b32 s19, 0x40400000
	s_mov_b32 s37, 0x41100000
	s_mov_b32 s41, 0x41300000
	s_mov_b32 s43, 0x41880000
	s_mov_b32 s45, 0x41980000
	s_mov_b32 s47, 0x41c80000
	s_mov_b32 s49, 0x41d80000
	s_mov_b32 s68, 0xc00000
	v_mov_b32_e32 v96, 0x42800000
	v_not_b32_e32 v97, 63
	v_mov_b32_e32 v98, 0xf149f2ca
	s_mov_b32 s101, 0
	s_branch .LBB0_624

; template <int TYPE>
; DI void attn_item(const Params& p, int layer, int head, int qt, int dil, int res, int chunk, char* smem) {
;     ...
;     __syncthreads();
;     if (TYPE == 2) {
;       if ((sflag[0] & sflag[1] & sflag[2] & sflag[3] & sflag[4] & sflag[5] & sflag[6] & sflag[7]) != 0) break;
;     }
;     *(uint4*)(sK + swz(kkey0, kchunk)) = kreg0;
;     ...
;     ATT_VSTORE(vreg0, vdc0)
;     __syncthreads();
;     ATT_PREFETCH((kt > kt_lo) ? kt - 1 : kt);
.LBB0_632:
	v_cmp_gt_i32_e32 vcc, v81, v99
	s_barrier
	s_nop 0
	v_subbrev_co_u32_e32 v32, vcc, 0, v81, vcc
	v_lshlrev_b32_e32 v34, 6, v32
	v_add_u32_e32 v32, v34, v100
	v_ashrrev_i32_e32 v33, 31, v32
	v_or_b32_e32 v34, v34, v75
	v_lshlrev_b64 v[32:33], v79, v[32:33]
	v_ashrrev_i32_e32 v35, 31, v34
	v_lshl_add_u64 v[32:33], v[32:33], 0, v[86:87]
	v_lshlrev_b64 v[34:35], v79, v[34:35]
	v_lshl_add_u64 v[34:35], v[34:35], 0, v[86:87]
	v_mad_u64_u32 v[36:37], s[0:1], v32, s62, v[88:89]
	v_mad_i32_i24 v37, v33, s62, v37
	v_mad_u64_u32 v[32:33], s[0:1], v34, s62, v[90:91]
	s_waitcnt vmcnt(0)
	ds_write_b128 v107, v[68:71]
	ds_write_b16 v108, v64 offset:8192
	ds_write_b16_d16_hi v108, v64 offset:8320
	ds_write_b16 v109, v65 offset:8192
	ds_write_b16_d16_hi v110, v65 offset:8192
	ds_write_b16 v111, v66 offset:8192
	ds_write_b16_d16_hi v112, v66 offset:8192
	ds_write_b16 v113, v67 offset:8192
	ds_write_b16_d16_hi v114, v67 offset:8192
	s_waitcnt lgkmcnt(0)
	s_barrier
	v_mad_i32_i24 v33, v35, s62, v33
	global_load_dwordx4 v[68:71], v[36:37], off
	global_load_dwordx4 v[64:67], v[32:33], off
	v_cmp_le_i32_e32 vcc, v81, v99
	s_and_b64 s[98:99], vcc, exec
	s_cbranch_scc0 .Llpf4_nl
	s_mov_b32 s101, 1
	s_and_saveexec_b64 s[98:99], s[8:9]
	s_cbranch_execz .Llpf4_sk
	v_mov_b32_e32 v254, 1
	global_atomic_add v255, v73, v254, s[4:5] sc0

; template <int TYPE>
; DI void attn_item(const Params& p, int layer, int head, int qt, int dil, int res, int chunk, char* smem) {
;     ...
;       const int Ks = Kb + 32 * sub;
;       bool need;
;       if (TYPE == 0) need = (Ks <= wq0 + 31) && (Ks + 31 >= wq0 - 128);
;       else if (TYPE == 1) need = (Ks <= wq0 + 31);
;       else need = (Ks < wq0 + 31) && (sflag[wid] == 0);
;       if (!need) continue;
;       const int db = Uq - Ks - 4 * h;
;       f32x16 s1, s2;
;       if (TYPE == 2) {
; #pragma unroll
;         for (int i = 0; i < 16; ++i) { s1[i] = 0.f; s2[i] = 0.f; }
;       } else {
;         const float base = -slope * (float)db - cref;
;         const bool msk = (TYPE == 0) ? true : (__builtin_amdgcn_readfirstlane((Ks + 31 > wq0) ? 1 : 0) != 0);
;         if (msk) {
; #pragma unroll
;           for (int i = 0; i < 16; ++i) {
;             const int ci = (i & 3) + 8 * (i >> 2);
;             const int dist = db - ci;
;             s1[i] = (dist >= 0 && dist <= wlim) ? fmaf(slope, (float)ci, base) : -1e30f;
;             s2[i] = s1[i];
;           }
;         } else {
; #pragma unroll
;           for (int i = 0; i < 16; ++i) {
;             const int ci = (i & 3) + 8 * (i >> 2);
;             s1[i] = fmaf(slope, (float)ci, base);
;             s2[i] = s1[i];
;           }
;         }
;       }
;       {
;         bf16x8 kf[4];
; #pragma unroll
;         for (int ks = 0; ks < 4; ++ks) kf[ks] = *(const bf16x8*)(sK + swz(32 * sub + ql, 2 * ks + h));
;         if (TYPE == 1) {
;           s1 = mfma32(kf[0], qf[0], s1);
;           s1 = mfma32(kf[1], qf[1], s1);
;           s2 = mfma32(kf[2], qf[2], s2);
;           s2 = mfma32(kf[3], qf[3], s2);
;         } else {
; #pragma unroll
;           for (int ks = 0; ks < 4; ++ks) s1 = mfma32(kf[ks], qf[ks], s1);
;         }
;       }
;       bf16x8 vf[2][2];
; #pragma unroll
;       for (int s = 0; s < 2; ++s)
; #pragma unroll
;         for (int dt = 0; dt < 2; ++dt) vf[s][dt] = *(const bf16x8*)(sV + swz(32 * dt + ql, 4 * sub + 2 * s + h));
;       if (TYPE == 0 || TYPE == 1) {
;         const bool masked = (TYPE == 0) ? true : (Ks + 31 > wq0);
;         bf16x8 pk0, pk1;
;         fx_step(s1, l1, db, masked, wlim, pk0, pk1);
;         O1a = mfma32(vf[0][0], pk0, O1a);
;         O1b = mfma32(vf[0][1], pk0, O1b);
;         O1a = mfma32(vf[1][0], pk1, O1a);
;         O1b = mfma32(vf[1][1], pk1, O1b);
.Llpf4_nl:
	v_add_u32_e32 v32, 1, v106
	v_cmp_le_i32_e64 s[0:1], v32, v101
	v_add_u32_e32 v32, 32, v106
	v_cmp_ge_i32_e64 s[2:3], v32, v102
	s_and_b64 s[0:1], s[0:1], s[2:3]
	s_and_saveexec_b64 s[2:3], s[0:1]
	s_cbranch_execz .LBB0_634
	v_add_u32_e32 v32, 1, v105
	v_cvt_f32_i32_e32 v33, v32
	v_cmp_gt_u32_e64 s[0:1], s67, v32
	v_add_u32_e32 v36, -2, v105
	v_add_u32_e32 v37, -1, v105
	v_fma_f32 v46, -v92, v33, -v104
	v_fma_f32 v33, 0, v92, v46
	v_add_f32_e32 v34, v92, v46
	v_cndmask_b32_e64 v32, v98, v33, s[0:1]
	v_cmp_gt_u32_e64 s[0:1], s67, v105
	v_add_u32_e32 v38, -8, v105
	v_add_u32_e32 v39, -7, v105
	v_cndmask_b32_e64 v33, v98, v34, s[0:1]
	v_pk_fma_f32 v[34:35], v[92:93], s[18:19], v[46:47] op_sel_hi:[1,1,0]
	v_cmp_gt_u32_e64 s[0:1], s67, v36
	v_add_u32_e32 v40, -10, v105
	v_add_u32_e32 v41, -9, v105
	v_cndmask_b32_e64 v35, v98, v35, s[0:1]
	v_cmp_gt_u32_e64 s[0:1], s67, v37
	v_pk_fma_f32 v[36:37], v[92:93], s[36:37], v[46:47] op_sel_hi:[1,1,0]
	v_add_u32_e32 v42, -16, v105
	v_cndmask_b32_e64 v34, v98, v34, s[0:1]
	v_cmp_gt_u32_e64 s[0:1], s67, v38
	v_add_u32_e32 v43, -15, v105
	ds_read_b128 v[120:123], v115 offset:4096
	v_cndmask_b32_e64 v37, v98, v37, s[0:1]
	v_cmp_gt_u32_e64 s[0:1], s67, v39
	v_pk_fma_f32 v[38:39], v[92:93], s[40:41], v[46:47] op_sel_hi:[1,1,0]
	v_subrev_u32_e32 v44, 18, v105
	v_cndmask_b32_e64 v36, v98, v36, s[0:1]
	v_cmp_gt_u32_e64 s[0:1], s67, v40
	v_subrev_u32_e32 v45, 17, v105
	v_subrev_u32_e32 v119, 23, v105
	v_cndmask_b32_e64 v39, v98, v39, s[0:1]
	v_cmp_gt_u32_e64 s[0:1], s67, v41
	v_pk_fma_f32 v[40:41], v[92:93], s[42:43], v[46:47] op_sel_hi:[1,1,0]
	v_subrev_u32_e32 v124, 25, v105
	v_cndmask_b32_e64 v38, v98, v38, s[0:1]
	v_cmp_gt_u32_e64 s[0:1], s67, v42
	s_nop 1
	v_cndmask_b32_e64 v41, v98, v41, s[0:1]
	v_cmp_gt_u32_e64 s[0:1], s67, v43
	v_pk_fma_f32 v[42:43], v[92:93], s[44:45], v[46:47] op_sel_hi:[1,1,0]
	v_subrev_u32_e32 v47, 24, v105
	v_cndmask_b32_e64 v40, v98, v40, s[0:1]
	v_cmp_gt_u32_e64 s[0:1], s67, v44
	s_nop 1
	v_cndmask_b32_e64 v43, v98, v43, s[0:1]
	v_cmp_gt_u32_e64 s[0:1], s67, v45
	v_pk_fma_f32 v[44:45], v[92:93], s[46:47], v[46:47] op_sel_hi:[1,1,0]
	s_nop 0
	v_cndmask_b32_e64 v42, v98, v42, s[0:1]
	v_cmp_gt_u32_e64 s[0:1], s67, v47
	v_pk_fma_f32 v[46:47], v[92:93], s[48:49], v[46:47] op_sel_hi:[1,1,0]
	s_nop 0
	v_cndmask_b32_e64 v45, v98, v45, s[0:1]
	v_cmp_gt_u32_e64 s[0:1], s67, v119
	v_subrev_u32_e32 v119, 26, v105
	s_nop 0
	v_cndmask_b32_e64 v44, v98, v44, s[0:1]
	v_cmp_gt_u32_e64 s[0:1], s67, v119
	s_nop 1
	v_cndmask_b32_e64 v47, v98, v47, s[0:1]
	v_cmp_gt_u32_e64 s[0:1], s67, v124
	ds_read_b128 v[124:127], v116 offset:4096
	s_nop 0
	v_cndmask_b32_e64 v46, v98, v46, s[0:1]
	s_waitcnt lgkmcnt(1)
	s_nop 0
	v_mfma_f32_32x32x16_bf16 v[32:47], v[120:123], v[48:51], v[32:47]
	s_waitcnt lgkmcnt(0)
	v_mfma_f32_32x32x16_bf16 v[32:47], v[124:127], v[52:55], v[32:47]
	ds_read_b128 v[120:123], v117 offset:4096
	ds_read_b128 v[124:127], v117 offset:8192
	s_waitcnt lgkmcnt(1)
	v_mfma_f32_32x32x16_bf16 v[32:47], v[120:123], v[56:59], v[32:47]
	ds_read_b128 v[120:123], v118 offset:4096
	ds_read_b128 v[128:131], v117 offset:12288
	s_waitcnt lgkmcnt(1)
	v_mfma_f32_32x32x16_bf16 v[32:47], v[120:123], v[60:63], v[32:47]
	ds_read_b128 v[120:123], v118 offset:8192
	ds_read_b128 v[132:135], v118 offset:12288
	s_nop 9
	v_exp_f32_e32 v32, v32
	v_exp_f32_e32 v33, v33
	v_exp_f32_e32 v34, v34
	v_exp_f32_e32 v35, v35
	v_exp_f32_e32 v36, v36
	v_exp_f32_e32 v37, v37
	v_exp_f32_e32 v38, v38
	v_exp_f32_e32 v39, v39
	v_add_f32_e32 v119, 0, v32
	v_add_f32_e32 v119, v33, v119
	v_add_f32_e32 v119, v34, v119
	v_add_f32_e32 v119, v35, v119
	v_cvt_pk_bf16_f32 v32, v32, v33
	v_cvt_pk_bf16_f32 v33, v34, v35
	v_cvt_pk_bf16_f32 v34, v36, v37
	v_cvt_pk_bf16_f32 v35, v38, v39
	v_add_f32_e32 v119, v36, v119
	v_add_f32_e32 v119, v37, v119
	v_mfma_f32_32x32x16_bf16 v[16:31], v[124:127], v[32:35], v[16:31]
	v_add_f32_e32 v36, v38, v119
	v_exp_f32_e32 v40, v40
	v_exp_f32_e32 v41, v41
	v_add_f32_e32 v36, v39, v36
	v_exp_f32_e32 v37, v42
	v_exp_f32_e32 v38, v43
	v_exp_f32_e32 v39, v44
	s_waitcnt lgkmcnt(2)
	v_mfma_f32_32x32x16_bf16 v[0:15], v[128:131], v[32:35], v[0:15]
	v_exp_f32_e32 v42, v45
	v_exp_f32_e32 v43, v46
	v_exp_f32_e32 v44, v47
	v_add_f32_e32 v36, v40, v36
	v_cvt_pk_bf16_f32 v32, v40, v41
	v_cvt_pk_bf16_f32 v33, v37, v38
	v_cvt_pk_bf16_f32 v34, v39, v42
	v_cvt_pk_bf16_f32 v35, v43, v44
	v_add_f32_e32 v36, v41, v36
	v_add_f32_e32 v36, v37, v36
	s_waitcnt lgkmcnt(1)
	v_mfma_f32_32x32x16_bf16 v[16:31], v[120:123], v[32:35], v[16:31]
	v_add_f32_e32 v36, v38, v36
	v_add_f32_e32 v36, v39, v36
	v_add_f32_e32 v36, v42, v36
	v_add_f32_e32 v36, v43, v36
	v_add_f32_e32 v36, v44, v36
	v_add_f32_e32 v103, v103, v36
	s_waitcnt lgkmcnt(0)
	v_mfma_f32_32x32x16_bf16 v[0:15], v[132:135], v[32:35], v[0:15]

; __global__ void __launch_bounds__(NTHR, 2) k_mega(Params p, int ph0, int ph1) {
;   __shared__ __attribute__((aligned(16))) char smem[SMEM_BYTES];
	.amdhsa_kernel _Z6k_mega6Paramsii
		.amdhsa_group_segment_fixed_size 147584
		.amdhsa_private_segment_fixed_size 0
		.amdhsa_kernarg_size 352
		.amdhsa_user_sgpr_count 2
		.amdhsa_user_sgpr_dispatch_ptr 0
		.amdhsa_user_sgpr_queue_ptr 0
		.amdhsa_user_sgpr_kernarg_segment_ptr 1
		.amdhsa_user_sgpr_dispatch_id 0
		.amdhsa_user_sgpr_kernarg_preload_length 0
		.amdhsa_user_sgpr_kernarg_preload_offset 0
		.amdhsa_user_sgpr_private_segment_size 0
		.amdhsa_uses_dynamic_stack 0
		.amdhsa_enable_private_segment 0
		.amdhsa_system_sgpr_workgroup_id_x 1
		.amdhsa_system_sgpr_workgroup_id_y 0
		.amdhsa_system_sgpr_workgroup_id_z 0
		.amdhsa_system_sgpr_workgroup_info 0
		.amdhsa_system_vgpr_workitem_id 2
		.amdhsa_next_free_vgpr 256
		.amdhsa_next_free_sgpr 102
		.amdhsa_accum_offset 256
		.amdhsa_reserve_vcc 1
		.amdhsa_float_round_mode_32 0
		.amdhsa_float_round_mode_16_64 0
		.amdhsa_float_denorm_mode_32 3
		.amdhsa_float_denorm_mode_16_64 3
		.amdhsa_dx10_clamp 1
		.amdhsa_ieee_mode 1
		.amdhsa_fp16_overflow 0
		.amdhsa_tg_split 0
		.amdhsa_exception_fp_ieee_invalid_op 0
		.amdhsa_exception_fp_denorm_src 0
		.amdhsa_exception_fp_ieee_div_zero 0
		.amdhsa_exception_fp_ieee_overflow 0
		.amdhsa_exception_fp_ieee_underflow 0
		.amdhsa_exception_fp_ieee_inexact 0
		.amdhsa_exception_int_div_zero 0
	.end_amdhsa_kernel

; __global__ void __launch_bounds__(NTHR, 2) k_mega(Params p, int ph0, int ph1) {
;   __shared__ __attribute__((aligned(16))) char smem[SMEM_BYTES];
amdhsa.kernels:
  - .agpr_count:     0
    .args:
      - .offset:         0
        .size:           88
        .value_kind:     by_value
      - .offset:         88
        .size:           4
        .value_kind:     by_value
      - .offset:         92
        .size:           4
        .value_kind:     by_value
      - .offset:         96
        .size:           4
        .value_kind:     hidden_block_count_x
      - .offset:         100
        .size:           4
        .value_kind:     hidden_block_count_y
      - .offset:         104
        .size:           4
        .value_kind:     hidden_block_count_z
      - .offset:         108
        .size:           2
        .value_kind:     hidden_group_size_x
      - .offset:         110
        .size:           2
        .value_kind:     hidden_group_size_y
      - .offset:         112
        .size:           2
        .value_kind:     hidden_group_size_z
      - .offset:         114
        .size:           2
        .value_kind:     hidden_remainder_x
      - .offset:         116
        .size:           2
        .value_kind:     hidden_remainder_y
      - .offset:         118
        .size:           2
        .value_kind:     hidden_remainder_z
      - .offset:         136
        .size:           8
        .value_kind:     hidden_global_offset_x
      - .offset:         144
        .size:           8
        .value_kind:     hidden_global_offset_y
      - .offset:         152
        .size:           8
        .value_kind:     hidden_global_offset_z
      - .offset:         160
        .size:           2
        .value_kind:     hidden_grid_dims
      - .offset:         184
        .size:           8
        .value_kind:     hidden_multigrid_sync_arg
    .group_segment_fixed_size: 147584
    .kernarg_segment_align: 8
    .kernarg_segment_size: 352
    .language:       OpenCL C
    .language_version:
      - 2
      - 0
    .max_flat_workgroup_size: 512
    .name:           _Z6k_mega6Paramsii
    .private_segment_fixed_size: 0
    .sgpr_count:     108
    .sgpr_spill_count: 1
    .symbol:         _Z6k_mega6Paramsii.kd
    .uniform_work_group_size: 1
    .uses_dynamic_stack: false
    .vgpr_count:     256
    .vgpr_spill_count: 0
    .wavefront_size: 64
